# NA item epilogue: lanes l and l+32 exchange halves (v_permlane32_swap) so each lane stores 16 contiguous bytes: 4 x dwordx4 instead of 8 x dwordx2 row-per-lane stores
# speedup vs baseline: 1.0082x; 1.0005x over previous
.LBB0_1068:
	v_mov_b32_e32 v2, v141
	s_nop 1
	v_permlane32_swap_b32_e32 v141, v2
	v_add_f32_e32 v2, v141, v2
	v_div_scale_f32 v3, s[12:13], v2, v2, 1.0
	v_rcp_f32_e32 v4, v3
	v_readlane_b32 s72, v239, 32
	v_lshlrev_b64 v[0:1], 10, v[102:103]
	v_readlane_b32 s73, v239, 33
	v_fma_f32 v5, -v3, v4, 1.0
	v_fmac_f32_e32 v4, v5, v4
	v_div_scale_f32 v5, vcc, 1.0, v2, 1.0
	v_mul_f32_e32 v6, v5, v4
	v_fma_f32 v7, -v3, v6, v5
	v_fmac_f32_e32 v6, v7, v4
	v_fma_f32 v3, -v3, v6, v5
	v_div_fmas_f32 v3, v3, v4, v6
	v_div_fixup_f32 v2, v3, v2, 1.0
	v_lshl_add_u64 v[0:1], v[0:1], 1, s[72:73]
	s_lshl_b32 s22, s46, 1
	v_lshl_add_u64 v[0:1], v[0:1], 0, s[22:23]
	v_lshl_add_u64 v[0:1], v[0:1], 0, v[88:89]
	v_mbcnt_lo_u32_b32 v170, -1, 0
	v_mbcnt_hi_u32_b32 v170, -1, v170
	v_lshrrev_b32_e32 v170, 5, v170
	v_lshlrev_b32_e32 v170, 3, v170
	v_mov_b32_e32 v171, 0
	v_lshl_add_u64 v[0:1], v[0:1], 0, v[170:171]
	v_pk_mul_f32 v[172:173], v[32:33], v[2:3] op_sel_hi:[1,0]
	v_pk_mul_f32 v[174:175], v[34:35], v[2:3] op_sel_hi:[1,0]
	v_cvt_pk_bf16_f32 v176, v172, v173
	v_cvt_pk_bf16_f32 v177, v174, v175
	v_pk_mul_f32 v[172:173], v[36:37], v[2:3] op_sel_hi:[1,0]
	v_pk_mul_f32 v[174:175], v[38:39], v[2:3] op_sel_hi:[1,0]
	v_cvt_pk_bf16_f32 v178, v172, v173
	v_cvt_pk_bf16_f32 v179, v174, v175
	s_nop 1
	v_permlane32_swap_b32_e32 v176, v178
	v_permlane32_swap_b32_e32 v177, v179
	global_store_dwordx4 v[0:1], v[176:179], off
	v_pk_mul_f32 v[184:185], v[40:41], v[2:3] op_sel_hi:[1,0]
	v_pk_mul_f32 v[186:187], v[42:43], v[2:3] op_sel_hi:[1,0]
	v_cvt_pk_bf16_f32 v180, v184, v185
	v_cvt_pk_bf16_f32 v181, v186, v187
	v_pk_mul_f32 v[184:185], v[44:45], v[2:3] op_sel_hi:[1,0]
	v_pk_mul_f32 v[186:187], v[46:47], v[2:3] op_sel_hi:[1,0]
	v_cvt_pk_bf16_f32 v182, v184, v185
	v_cvt_pk_bf16_f32 v183, v186, v187
	s_nop 1
	v_permlane32_swap_b32_e32 v180, v182
	v_permlane32_swap_b32_e32 v181, v183
	global_store_dwordx4 v[0:1], v[180:183], off offset:32
	v_pk_mul_f32 v[172:173], v[48:49], v[2:3] op_sel_hi:[1,0]
	v_pk_mul_f32 v[174:175], v[50:51], v[2:3] op_sel_hi:[1,0]
	v_cvt_pk_bf16_f32 v176, v172, v173
	v_cvt_pk_bf16_f32 v177, v174, v175
	v_pk_mul_f32 v[172:173], v[52:53], v[2:3] op_sel_hi:[1,0]
	v_pk_mul_f32 v[174:175], v[54:55], v[2:3] op_sel_hi:[1,0]
	v_cvt_pk_bf16_f32 v178, v172, v173
	v_cvt_pk_bf16_f32 v179, v174, v175
	s_nop 1
	v_permlane32_swap_b32_e32 v176, v178
	v_permlane32_swap_b32_e32 v177, v179
	global_store_dwordx4 v[0:1], v[176:179], off offset:64
	v_pk_mul_f32 v[184:185], v[56:57], v[2:3] op_sel_hi:[1,0]
	v_pk_mul_f32 v[186:187], v[58:59], v[2:3] op_sel_hi:[1,0]
	v_cvt_pk_bf16_f32 v180, v184, v185
	v_cvt_pk_bf16_f32 v181, v186, v187
	v_pk_mul_f32 v[184:185], v[60:61], v[2:3] op_sel_hi:[1,0]
	v_pk_mul_f32 v[186:187], v[62:63], v[2:3] op_sel_hi:[1,0]
	v_cvt_pk_bf16_f32 v182, v184, v185
	v_cvt_pk_bf16_f32 v183, v186, v187
	s_nop 1
	v_permlane32_swap_b32_e32 v180, v182
	v_permlane32_swap_b32_e32 v181, v183
	global_store_dwordx4 v[0:1], v[180:183], off offset:96
	s_add_i32 s45, s45, s14
	s_add_i32 s44, s44, s14
	s_cmpk_lt_i32 s45, 0x800
	v_readlane_b32 s74, v239, 34
	v_readlane_b32 s75, v239, 35
	v_readlane_b32 s76, v239, 36
	v_readlane_b32 s77, v239, 37
	v_readlane_b32 s78, v239, 38
	v_readlane_b32 s79, v239, 39
	s_waitcnt lgkmcnt(0)
	s_barrier
	s_cbranch_scc0 .LBB0_1130
